# mLSTM item prologue: gate loads for all four scan rounds issued up front (three exposed global round trips removed)
# speedup vs baseline: 1.0042x; 1.0042x over previous
.LBB0_170:
	s_and_b64 vcc, exec, s[12:13]
	s_cbranch_vccz .LBB0_136
	v_readfirstlane_b32 s2, v222
	s_mov_b64 s[12:13], exec
	v_readlane_b32 s4, v254, 16
	v_readlane_b32 s5, v254, 17
	s_and_b64 s[4:5], s[12:13], s[4:5]
	s_mov_b64 exec, s[4:5]
	ds_write_b32 v223, v97
	s_or_b64 exec, exec, s[12:13]
	s_ashr_i32 s19, s18, 31
	s_ashr_i32 s82, s18, 2
	s_lshr_b32 s12, s2, 6
	s_lshl_b64 s[88:89], s[18:19], 15
	s_and_b32 s4, s18, 3
	v_readlane_b32 s3, v250, 42
	s_add_u32 s20, s3, s88
	v_readlane_b32 s3, v250, 43
	s_addc_u32 s21, s3, s89
	v_mov_b32_e32 v5, v222
	s_ashr_i32 s83, s82, 31
	s_lshl_b64 s[18:19], s[82:83], 11
	v_and_b32_e32 v4, 63, v5
	v_or_b32_e32 v0, s18, v4
	v_mov_b32_e32 v1, s19
	s_and_b32 s90, s2, 0xffffffc0
	s_mov_b32 s91, s37
	v_lshl_add_u64 v[2:3], v[0:1], 0, s[90:91]
	v_readlane_b32 s16, v250, 25
	v_lshlrev_b64 v[2:3], 7, v[2:3]
	v_readlane_b32 s17, v250, 26
	s_lshl_b32 s36, s4, 2
	v_add_u32_e32 v7, -1, v227
	v_lshl_add_u64 v[2:3], s[16:17], 0, v[2:3]
	v_lshl_add_u64 v[2:3], v[2:3], 0, s[36:37]
	global_load_dword v13, v[2:3], off sc1
	global_load_dword v8, v[2:3], off offset:16 sc1
	s_mov_b64 s[42:43], 0x10000
	v_lshl_add_u64 v[30:31], v[2:3], 0, s[42:43]
	global_load_dword v32, v[30:31], off sc1
	global_load_dword v33, v[30:31], off offset:16 sc1
	v_lshl_add_u64 v[30:31], v[30:31], 0, s[42:43]
	global_load_dword v34, v[30:31], off sc1
	global_load_dword v35, v[30:31], off offset:16 sc1
	v_lshl_add_u64 v[30:31], v[30:31], 0, s[42:43]
	global_load_dword v36, v[30:31], off sc1
	global_load_dword v37, v[30:31], off offset:16 sc1
	v_and_b32_e32 v2, 64, v227
	v_cmp_lt_i32_e32 vcc, v7, v2
	v_add_u32_e32 v11, -2, v227
	v_add_u32_e32 v9, -4, v227
	v_cndmask_b32_e32 v7, v7, v227, vcc
	v_lshlrev_b32_e32 v7, 2, v7
	v_cmp_lt_i32_e64 s[42:43], v9, v2
	v_cmp_gt_u32_e64 s[44:45], 2, v4
	v_add_u32_e32 v10, -8, v227
	v_cndmask_b32_e64 v9, v9, v227, s[42:43]
	v_lshlrev_b32_e32 v9, 2, v9
	v_cmp_lt_i32_e64 s[42:43], v10, v2
	v_cmp_gt_u32_e64 s[46:47], 4, v4
	v_bfrev_b32_e32 v3, 0.5
	v_cndmask_b32_e64 v10, v10, v227, s[42:43]
	v_lshlrev_b32_e32 v10, 2, v10
	v_lshl_or_b32 v6, v227, 2, v3
	v_add_u32_e32 v3, -16, v227
	v_cmp_lt_i32_e64 s[42:43], v3, v2
	v_cmp_gt_u32_e64 s[48:49], 8, v4
	v_cmp_gt_u32_e64 s[50:51], 16, v4
	v_cndmask_b32_e64 v3, v3, v227, s[42:43]
	v_lshlrev_b32_e32 v96, 2, v4
	s_lshl_b32 s14, s12, 8
	s_mov_b32 s15, s37
	s_waitcnt vmcnt(0)
	v_mul_f32_e64 v12, |v8|, s94
	v_fma_f32 v14, |v8|, s94, -v12
	v_rndne_f32_e32 v15, v12
	v_fma_f32 v14, |v8|, s39, v14
	v_sub_f32_e32 v12, v12, v15
	v_add_f32_e32 v12, v12, v14
	v_cvt_i32_f32_e32 v15, v15
	v_exp_f32_e32 v12, v12
	v_cmp_ngt_f32_e64 vcc, |v8|, s22
	v_max_f32_e32 v14, v8, v8
	v_min_f32_e32 v16, 0, v14
	v_ldexp_f32 v12, v12, v15
	v_cndmask_b32_e32 v12, 0, v12, vcc
	v_cmp_nlt_f32_e64 vcc, |v8|, s23
	s_nop 1
	v_cndmask_b32_e32 v8, v229, v12, vcc
	v_add_f32_e32 v12, 1.0, v8
	v_add_f32_e32 v17, -1.0, v12
	v_frexp_mant_f32_e32 v18, v12
	v_cvt_f64_f32_e32 v[14:15], v12
	v_sub_f32_e32 v19, v17, v12
	v_frexp_exp_i32_f64_e32 v14, v[14:15]
	v_cmp_gt_f32_e32 vcc, s60, v18
	v_sub_f32_e32 v17, v8, v17
	v_add_f32_e32 v15, 1.0, v19
	v_subbrev_co_u32_e32 v14, vcc, 0, v14, vcc
	v_add_f32_e32 v15, v17, v15
	v_sub_u32_e32 v17, 0, v14
	v_cvt_f32_i32_e32 v14, v14
	v_ldexp_f32 v12, v12, v17
	v_ldexp_f32 v15, v15, v17
	v_add_f32_e32 v17, -1.0, v12
	v_add_f32_e32 v18, 1.0, v12
	v_add_f32_e32 v19, 1.0, v17
	v_add_f32_e32 v20, -1.0, v18
	v_sub_f32_e32 v19, v12, v19
	v_sub_f32_e32 v12, v12, v20
	v_mul_f32_e32 v20, 0x3f317218, v14
	v_add_f32_e32 v19, v15, v19
	v_add_f32_e32 v12, v15, v12
	v_fma_f32 v15, v14, s61, -v20
	v_add_f32_e32 v21, v17, v19
	v_add_f32_e32 v22, v18, v12
	v_fmac_f32_e32 v15, 0xb102e308, v14
	v_sub_f32_e32 v14, v17, v21
	v_sub_f32_e32 v17, v18, v22
	v_rcp_f32_e32 v18, v22
	v_add_f32_e32 v23, v20, v15
	v_add_f32_e32 v12, v12, v17
	v_sub_f32_e32 v17, v23, v20
	v_sub_f32_e32 v15, v15, v17
	v_mul_f32_e32 v17, v21, v18
	v_add_f32_e32 v14, v19, v14
	v_mul_f32_e32 v19, v22, v17
	v_fma_f32 v20, v17, v22, -v19
	v_fmac_f32_e32 v20, v17, v12
	v_add_f32_e32 v24, v19, v20
	v_sub_f32_e32 v25, v21, v24
	v_sub_f32_e32 v19, v24, v19
	v_sub_f32_e32 v21, v21, v25
	v_sub_f32_e32 v19, v19, v20
	v_sub_f32_e32 v20, v21, v24
	v_add_f32_e32 v14, v14, v20
	v_add_f32_e32 v14, v19, v14
	v_add_f32_e32 v19, v25, v14
	v_mul_f32_e32 v20, v18, v19
	v_sub_f32_e32 v21, v25, v19
	v_mul_f32_e32 v24, v22, v20
	v_add_f32_e32 v14, v14, v21
	v_add_f32_e32 v21, v17, v20
	v_fma_f32 v22, v20, v22, -v24
	v_sub_f32_e32 v17, v21, v17
	v_fmac_f32_e32 v22, v20, v12
	v_sub_f32_e32 v12, v20, v17
	v_add_f32_e32 v17, v24, v22
	v_sub_f32_e32 v20, v17, v24
	v_sub_f32_e32 v24, v19, v17
	v_sub_f32_e32 v19, v19, v24
	v_sub_f32_e32 v17, v19, v17
	v_sub_f32_e32 v20, v20, v22
	v_add_f32_e32 v14, v14, v17
	v_add_f32_e32 v14, v20, v14
	v_add_f32_e32 v14, v24, v14
	v_mul_f32_e32 v14, v18, v14
	v_add_f32_e32 v12, v12, v14
	v_add_f32_e32 v14, v21, v12
	v_mul_f32_e32 v17, v14, v14
	v_fmamk_f32 v20, v17, 0x3e9b6dac, v226
	v_sub_f32_e32 v18, v14, v21
	v_ldexp_f32 v19, v14, 1
	v_mul_f32_e32 v14, v14, v17
	v_fmaak_f32 v17, v17, v20, 0x3f2aaada
	v_mul_f32_e32 v14, v14, v17
	v_add_f32_e32 v17, v19, v14
	v_sub_f32_e32 v12, v12, v18
	v_sub_f32_e32 v18, v17, v19
	v_ldexp_f32 v12, v12, 1
	v_sub_f32_e32 v14, v14, v18
	v_add_f32_e32 v12, v12, v14
	v_add_f32_e32 v14, v17, v12
	v_sub_f32_e32 v17, v14, v17
	v_add_f32_e32 v18, v23, v14
	v_sub_f32_e32 v12, v12, v17
	v_sub_f32_e32 v17, v18, v23
	v_sub_f32_e32 v19, v18, v17
	v_sub_f32_e32 v14, v14, v17
	v_add_f32_e32 v17, v15, v12
	v_sub_f32_e32 v19, v23, v19
	v_sub_f32_e32 v20, v17, v15
	v_add_f32_e32 v14, v14, v19
	v_sub_f32_e32 v19, v17, v20
	v_sub_f32_e32 v12, v12, v20
	v_sub_f32_e32 v15, v15, v19
	v_add_f32_e32 v14, v17, v14
	v_add_f32_e32 v12, v12, v15
	v_add_f32_e32 v15, v18, v14
	v_sub_f32_e32 v17, v15, v18
	v_sub_f32_e32 v14, v14, v17
	v_add_f32_e32 v12, v12, v14
	v_add_f32_e32 v12, v15, v12
	v_cmp_neq_f32_e32 vcc, s25, v8
	v_subrev_u32_e32 v15, 32, v227
	v_cmp_lt_i32_e64 s[42:43], v15, v2
	v_cndmask_b32_e32 v12, v229, v12, vcc
	v_cmp_lt_f32_e64 vcc, |v8|, s95
	v_add_u32_e32 v19, 64, v2
	v_xor_b32_e32 v18, 4, v227
	v_cndmask_b32_e32 v8, v12, v8, vcc
	v_sub_f32_e32 v12, v16, v8
	ds_bpermute_b32 v14, v7, v12
	v_cmp_lt_i32_e32 vcc, v11, v2
	v_cndmask_b32_e64 v2, v15, v227, s[42:43]
	v_xor_b32_e32 v16, 2, v227
	v_cndmask_b32_e32 v8, v11, v227, vcc
	s_waitcnt lgkmcnt(0)
	v_add_f32_e32 v11, v12, v14
	v_cmp_eq_u32_e32 vcc, 0, v4
	v_lshlrev_b32_e32 v8, 2, v8
	v_xor_b32_e32 v14, 1, v227
	v_cndmask_b32_e32 v11, v11, v12, vcc
	ds_bpermute_b32 v12, v8, v11
	v_cmp_lt_i32_e64 s[42:43], v14, v19
	v_cmp_lt_i32_e64 s[52:53], v18, v19
	s_waitcnt lgkmcnt(0)
	v_add_f32_e32 v12, v11, v12
	v_cndmask_b32_e64 v11, v12, v11, s[44:45]
	ds_bpermute_b32 v12, v9, v11
	v_cndmask_b32_e64 v15, v227, v14, s[42:43]
	v_cmp_lt_i32_e64 s[42:43], v16, v19
	v_lshlrev_b32_e32 v189, 2, v15
	s_waitcnt lgkmcnt(0)
	v_add_f32_e32 v12, v11, v12
	v_cndmask_b32_e64 v12, v12, v11, s[46:47]
	ds_bpermute_b32 v17, v10, v12
	v_lshlrev_b32_e32 v11, 2, v3
	v_cndmask_b32_e64 v16, v227, v16, s[42:43]
	v_cmp_gt_u32_e64 s[42:43], 32, v4
	v_lshlrev_b32_e32 v191, 2, v16
	s_waitcnt lgkmcnt(0)
	v_add_f32_e32 v3, v12, v17
	v_cndmask_b32_e64 v3, v3, v12, s[48:49]
	ds_bpermute_b32 v17, v11, v3
	v_lshlrev_b32_e32 v12, 2, v2
	s_waitcnt lgkmcnt(0)
	v_add_f32_e32 v2, v3, v17
	v_cndmask_b32_e64 v2, v2, v3, s[50:51]
	ds_bpermute_b32 v3, v12, v2
	s_waitcnt lgkmcnt(0)
	v_add_f32_e32 v3, v2, v3
	v_cndmask_b32_e64 v17, v3, v2, s[42:43]
	v_sub_f32_e32 v20, v13, v17
	ds_bpermute_b32 v2, v7, v20
	ds_bpermute_b32 v14, v6, v17
	v_cndmask_b32_e64 v3, v227, v18, s[52:53]
	v_lshlrev_b32_e32 v209, 2, v3
	s_waitcnt lgkmcnt(1)
	v_max_f32_e32 v2, v2, v2
	v_max_f32_e32 v2, v20, v2
	v_cndmask_b32_e32 v2, v2, v20, vcc
	ds_bpermute_b32 v18, v8, v2
	s_waitcnt lgkmcnt(1)
	v_sub_f32_e32 v15, v14, v17
	v_add_f32_e32 v15, v15, v13
	ds_bpermute_b32 v21, v189, v15
	s_waitcnt lgkmcnt(1)
	v_max_f32_e32 v18, v18, v18
	v_max_f32_e32 v18, v2, v18
	v_cndmask_b32_e64 v2, v18, v2, s[44:45]
	s_waitcnt lgkmcnt(0)
	v_max_f32_e32 v16, v21, v21
	ds_bpermute_b32 v18, v9, v2
	v_max_f32_e32 v15, v15, v16
	ds_bpermute_b32 v16, v191, v15
	s_waitcnt lgkmcnt(1)
	v_max_f32_e32 v18, v18, v18
	v_max_f32_e32 v18, v2, v18
	s_waitcnt lgkmcnt(0)
	v_max_f32_e32 v3, v16, v16
	v_cndmask_b32_e64 v2, v18, v2, s[46:47]
	v_max_f32_e32 v3, v15, v3
	ds_bpermute_b32 v18, v10, v2
	ds_bpermute_b32 v15, v209, v3
	s_waitcnt lgkmcnt(1)
	v_max_f32_e32 v16, v18, v18
	s_waitcnt lgkmcnt(0)
	v_max_f32_e32 v15, v15, v15
	v_max_f32_e32 v16, v2, v16
	v_max_f32_e32 v3, v3, v15
	v_xor_b32_e32 v15, 8, v227
	v_cndmask_b32_e64 v2, v16, v2, s[48:49]
	v_cmp_lt_i32_e64 s[52:53], v15, v19
	ds_bpermute_b32 v16, v11, v2
	s_waitcnt lgkmcnt(0)
	v_max_f32_e32 v16, v16, v16
	v_cndmask_b32_e64 v15, v227, v15, s[52:53]
	v_lshlrev_b32_e32 v210, 2, v15
	ds_bpermute_b32 v15, v210, v3
	v_max_f32_e32 v16, v2, v16
	v_cndmask_b32_e64 v18, v16, v2, s[50:51]
	ds_bpermute_b32 v16, v12, v18
	v_max_f32_e32 v22, v18, v18
	s_waitcnt lgkmcnt(1)
	v_max_f32_e32 v2, v15, v15
	v_max_f32_e32 v15, v3, v2
	v_xor_b32_e32 v2, 16, v227
	v_cmp_lt_i32_e64 s[52:53], v2, v19
	s_waitcnt lgkmcnt(0)
	v_max_f32_e32 v16, v16, v16
	v_max_f32_e32 v22, v22, v16
	v_cndmask_b32_e64 v2, v227, v2, s[52:53]
	v_lshlrev_b32_e32 v211, 2, v2
	ds_bpermute_b32 v21, v211, v15
	v_lshl_add_u64 v[2:3], s[20:21], 0, v[96:97]
	s_waitcnt lgkmcnt(0)
	v_max_f32_e32 v16, v21, v21
	v_max_f32_e32 v15, v15, v16
	v_xor_b32_e32 v16, 32, v227
	v_cmp_lt_i32_e64 s[52:53], v16, v19
	v_cndmask_b32_e64 v21, v22, v18, s[42:43]
	v_lshl_add_u64 v[18:19], s[14:15], 2, v[2:3]
	v_cndmask_b32_e64 v16, v227, v16, s[52:53]
	v_lshlrev_b32_e32 v212, 2, v16
	ds_bpermute_b32 v16, v212, v15
	global_store_dword v[18:19], v17, off sc1
	global_store_dword v[18:19], v20, off offset:256 sc1
	global_store_dword v[18:19], v21, off offset:512 sc1
	global_store_dword v[18:19], v13, off offset:768 sc1
	s_and_saveexec_b64 s[52:53], vcc
	s_movk_i32 s85, 0x210
	s_cbranch_execz .LBB0_175
	s_lshl_b32 s3, s12, 2
	s_add_i32 s3, s3, 0
	s_add_i32 s5, s3, 0x21900
	s_waitcnt lgkmcnt(0)
	v_max_f32_e32 v13, v16, v16
	v_max_f32_e32 v15, v15, v15
	s_add_i32 s3, s3, 0x21980
	v_max_f32_e32 v13, v15, v13
	v_mov_b32_e32 v15, s5
	ds_write_b32 v15, v14
	v_mov_b32_e32 v14, s3
	ds_write_b32 v14, v13
.LBB0_175:
	s_or_b64 exec, exec, s[52:53]
	s_add_i32 s3, s12, 8
	s_lshl_b32 s14, s3, 6
	s_mov_b32 s15, s37
	v_lshl_add_u64 v[14:15], v[0:1], 0, s[14:15]
	v_lshlrev_b64 v[14:15], 7, v[14:15]
	v_lshl_add_u64 v[14:15], s[16:17], 0, v[14:15]
	v_lshl_add_u64 v[14:15], v[14:15], 0, s[36:37]
	v_mov_b32_e32 v13, v32
	s_nop 0
	v_mov_b32_e32 v15, v33
	s_waitcnt vmcnt(0) lgkmcnt(0)
	v_mul_f32_e64 v16, |v15|, s94
	v_fma_f32 v17, |v15|, s94, -v16
	v_rndne_f32_e32 v18, v16
	v_fma_f32 v17, |v15|, s39, v17
	v_sub_f32_e32 v16, v16, v18
	v_add_f32_e32 v16, v16, v17
	v_exp_f32_e32 v16, v16
	v_cvt_i32_f32_e32 v17, v18
	v_cmp_ngt_f32_e64 s[52:53], |v15|, s22
	v_max_f32_e32 v14, v15, v15
	v_min_f32_e32 v14, 0, v14
	v_ldexp_f32 v16, v16, v17
	v_cndmask_b32_e64 v16, 0, v16, s[52:53]
	v_cmp_nlt_f32_e64 s[52:53], |v15|, s23
	s_nop 1
	v_cndmask_b32_e64 v15, v229, v16, s[52:53]
	v_add_f32_e32 v18, 1.0, v15
	v_add_f32_e32 v16, -1.0, v18
	v_sub_f32_e32 v17, v16, v18
	v_add_f32_e32 v17, 1.0, v17
	v_sub_f32_e32 v16, v15, v16
	v_add_f32_e32 v19, v16, v17
	v_frexp_mant_f32_e32 v16, v18
	v_cmp_gt_f32_e64 s[52:53], s60, v16
	v_cvt_f64_f32_e32 v[16:17], v18
	v_frexp_exp_i32_f64_e32 v16, v[16:17]
	v_subbrev_co_u32_e64 v16, s[52:53], 0, v16, s[52:53]
	v_sub_u32_e32 v17, 0, v16
	v_ldexp_f32 v18, v18, v17
	v_ldexp_f32 v17, v19, v17
	v_add_f32_e32 v19, -1.0, v18
	v_add_f32_e32 v20, 1.0, v19
	v_sub_f32_e32 v20, v18, v20
	v_add_f32_e32 v20, v17, v20
	v_add_f32_e32 v21, v19, v20
	v_sub_f32_e32 v19, v19, v21
	v_add_f32_e32 v19, v20, v19
	v_add_f32_e32 v20, 1.0, v18
	v_add_f32_e32 v22, -1.0, v20
	v_sub_f32_e32 v18, v18, v22
	v_add_f32_e32 v17, v17, v18
	v_add_f32_e32 v18, v20, v17
	v_sub_f32_e32 v20, v20, v18
	v_add_f32_e32 v17, v17, v20
	v_rcp_f32_e32 v20, v18
	v_cvt_f32_i32_e32 v16, v16
	v_cmp_neq_f32_e64 s[52:53], s25, v15
	v_mul_f32_e32 v22, v21, v20
	v_mul_f32_e32 v23, v18, v22
	v_fma_f32 v24, v22, v18, -v23
	v_fmac_f32_e32 v24, v22, v17
	v_add_f32_e32 v25, v23, v24
	v_sub_f32_e32 v26, v21, v25
	v_sub_f32_e32 v21, v21, v26
	v_sub_f32_e32 v23, v25, v23
	v_sub_f32_e32 v21, v21, v25
	v_add_f32_e32 v19, v19, v21
	v_sub_f32_e32 v21, v23, v24
	v_add_f32_e32 v19, v21, v19
	v_add_f32_e32 v21, v26, v19
	v_mul_f32_e32 v23, v20, v21
	v_mul_f32_e32 v24, v18, v23
	v_fma_f32 v18, v23, v18, -v24
	v_fmac_f32_e32 v18, v23, v17
	v_sub_f32_e32 v17, v26, v21
	v_add_f32_e32 v17, v19, v17
	v_add_f32_e32 v19, v24, v18
	v_sub_f32_e32 v25, v21, v19
	v_sub_f32_e32 v21, v21, v25
	v_sub_f32_e32 v24, v19, v24
	v_sub_f32_e32 v19, v21, v19
	v_add_f32_e32 v17, v17, v19
	v_sub_f32_e32 v18, v24, v18
	v_add_f32_e32 v17, v18, v17
	v_add_f32_e32 v18, v22, v23
	v_add_f32_e32 v17, v25, v17
	v_sub_f32_e32 v19, v18, v22
	v_mul_f32_e32 v17, v20, v17
	v_sub_f32_e32 v19, v23, v19
	v_add_f32_e32 v17, v19, v17
	v_mul_f32_e32 v22, 0x3f317218, v16
	v_add_f32_e32 v19, v18, v17
	v_fma_f32 v23, v16, s61, -v22
	v_mul_f32_e32 v20, v19, v19
	v_fmac_f32_e32 v23, 0xb102e308, v16
	v_sub_f32_e32 v16, v19, v18
	v_fmamk_f32 v21, v20, 0x3e9b6dac, v226
	v_sub_f32_e32 v16, v17, v16
	v_add_f32_e32 v17, v22, v23
	v_fmaak_f32 v21, v20, v21, 0x3f2aaada
	v_sub_f32_e32 v18, v17, v22
	v_ldexp_f32 v22, v19, 1
	v_mul_f32_e32 v19, v19, v20
	v_mul_f32_e32 v19, v19, v21
	v_add_f32_e32 v20, v22, v19
	v_sub_f32_e32 v21, v20, v22
	v_ldexp_f32 v16, v16, 1
	v_sub_f32_e32 v19, v19, v21
	v_add_f32_e32 v16, v16, v19
	v_add_f32_e32 v19, v20, v16
	v_sub_f32_e32 v20, v19, v20
	v_sub_f32_e32 v16, v16, v20
	v_add_f32_e32 v20, v17, v19
	v_sub_f32_e32 v21, v20, v17
	v_sub_f32_e32 v22, v20, v21
	v_sub_f32_e32 v18, v23, v18
	v_sub_f32_e32 v17, v17, v22
	v_sub_f32_e32 v19, v19, v21
	v_add_f32_e32 v17, v19, v17
	v_add_f32_e32 v19, v18, v16
	v_sub_f32_e32 v21, v19, v18
	v_sub_f32_e32 v22, v19, v21
	v_sub_f32_e32 v18, v18, v22
	v_sub_f32_e32 v16, v16, v21
	v_add_f32_e32 v17, v19, v17
	v_add_f32_e32 v16, v16, v18
	v_add_f32_e32 v18, v20, v17
	v_sub_f32_e32 v19, v18, v20
	v_sub_f32_e32 v17, v17, v19
	v_add_f32_e32 v16, v16, v17
	v_add_f32_e32 v16, v18, v16
	v_cndmask_b32_e64 v16, v229, v16, s[52:53]
	v_cmp_lt_f32_e64 s[52:53], |v15|, s95
	s_nop 1
	v_cndmask_b32_e64 v15, v16, v15, s[52:53]
	v_sub_f32_e32 v14, v14, v15
	ds_bpermute_b32 v15, v7, v14
	s_lshl_b32 s52, s3, 8
	s_mov_b32 s53, s37
	s_waitcnt lgkmcnt(0)
	v_add_f32_e32 v15, v14, v15
	v_cndmask_b32_e32 v14, v15, v14, vcc
	ds_bpermute_b32 v15, v8, v14
	s_waitcnt lgkmcnt(0)
	v_add_f32_e32 v15, v14, v15
	v_cndmask_b32_e64 v14, v15, v14, s[44:45]
	ds_bpermute_b32 v15, v9, v14
	s_waitcnt lgkmcnt(0)
	v_add_f32_e32 v15, v14, v15
	v_cndmask_b32_e64 v14, v15, v14, s[46:47]
	ds_bpermute_b32 v15, v10, v14
	s_waitcnt lgkmcnt(0)
	v_add_f32_e32 v15, v14, v15
	v_cndmask_b32_e64 v14, v15, v14, s[48:49]
	ds_bpermute_b32 v15, v11, v14
	s_waitcnt lgkmcnt(0)
	v_add_f32_e32 v15, v14, v15
	v_cndmask_b32_e64 v14, v15, v14, s[50:51]
	ds_bpermute_b32 v15, v12, v14
	s_waitcnt lgkmcnt(0)
	v_add_f32_e32 v15, v14, v15
	v_cndmask_b32_e64 v17, v15, v14, s[42:43]
	v_sub_f32_e32 v20, v13, v17
	ds_bpermute_b32 v14, v7, v20
	s_waitcnt lgkmcnt(0)
	v_max_f32_e32 v14, v14, v14
	v_max_f32_e32 v14, v20, v14
	v_cndmask_b32_e32 v14, v14, v20, vcc
	ds_bpermute_b32 v15, v8, v14
	s_waitcnt lgkmcnt(0)
	v_max_f32_e32 v15, v15, v15
	v_max_f32_e32 v15, v14, v15
	v_cndmask_b32_e64 v14, v15, v14, s[44:45]
	ds_bpermute_b32 v15, v9, v14
	s_waitcnt lgkmcnt(0)
	v_max_f32_e32 v15, v15, v15
	v_max_f32_e32 v15, v14, v15
	v_cndmask_b32_e64 v14, v15, v14, s[46:47]
	ds_bpermute_b32 v15, v10, v14
	s_waitcnt lgkmcnt(0)
	v_max_f32_e32 v15, v15, v15
	v_max_f32_e32 v15, v14, v15
	v_cndmask_b32_e64 v14, v15, v14, s[48:49]
	ds_bpermute_b32 v15, v11, v14
	s_waitcnt lgkmcnt(0)
	v_max_f32_e32 v15, v15, v15
	v_max_f32_e32 v15, v14, v15
	v_cndmask_b32_e64 v18, v15, v14, s[50:51]
	ds_bpermute_b32 v14, v12, v18
	v_max_f32_e32 v15, v18, v18
	s_waitcnt lgkmcnt(0)
	v_max_f32_e32 v14, v14, v14
	v_max_f32_e32 v19, v15, v14
	ds_bpermute_b32 v14, v6, v17
	v_cndmask_b32_e64 v21, v19, v18, s[42:43]
	v_lshl_add_u64 v[18:19], s[52:53], 2, v[2:3]
	global_store_dword v[18:19], v17, off sc1
	global_store_dword v[18:19], v20, off offset:256 sc1
	global_store_dword v[18:19], v21, off offset:512 sc1
	global_store_dword v[18:19], v13, off offset:768 sc1
	s_waitcnt lgkmcnt(0)
	v_sub_f32_e32 v15, v14, v17
	v_add_f32_e32 v15, v15, v13
	ds_bpermute_b32 v16, v189, v15
	s_waitcnt lgkmcnt(0)
	v_max_f32_e32 v16, v16, v16
	v_max_f32_e32 v15, v15, v16
	ds_bpermute_b32 v16, v191, v15
	s_waitcnt lgkmcnt(0)
	v_max_f32_e32 v16, v16, v16
	v_max_f32_e32 v15, v15, v16
	ds_bpermute_b32 v16, v209, v15
	s_waitcnt lgkmcnt(0)
	v_max_f32_e32 v16, v16, v16
	v_max_f32_e32 v15, v15, v16
	ds_bpermute_b32 v16, v210, v15
	s_waitcnt lgkmcnt(0)
	v_max_f32_e32 v16, v16, v16
	v_max_f32_e32 v15, v15, v16
	ds_bpermute_b32 v16, v211, v15
	s_waitcnt lgkmcnt(0)
	v_max_f32_e32 v16, v16, v16
	v_max_f32_e32 v15, v15, v16
	ds_bpermute_b32 v16, v212, v15
	s_and_saveexec_b64 s[52:53], vcc
	s_cbranch_execz .LBB0_177
	s_lshl_b32 s3, s3, 2
	s_add_i32 s3, s3, 0
	s_add_i32 s5, s3, 0x21900
	s_waitcnt lgkmcnt(0)
	v_max_f32_e32 v13, v16, v16
	v_max_f32_e32 v15, v15, v15
	s_add_i32 s3, s3, 0x21980
	v_max_f32_e32 v13, v15, v13
	v_mov_b32_e32 v15, s5
	ds_write_b32 v15, v14
	v_mov_b32_e32 v14, s3
	ds_write_b32 v14, v13
.LBB0_177:
	s_or_b64 exec, exec, s[52:53]
	s_add_i32 s3, s12, 16
	s_lshl_b32 s14, s3, 6
	s_mov_b32 s15, s37
	v_lshl_add_u64 v[14:15], v[0:1], 0, s[14:15]
	v_lshlrev_b64 v[14:15], 7, v[14:15]
	v_lshl_add_u64 v[14:15], s[16:17], 0, v[14:15]
	v_lshl_add_u64 v[14:15], v[14:15], 0, s[36:37]
	v_mov_b32_e32 v13, v34
	s_nop 0
	v_mov_b32_e32 v15, v35
	s_waitcnt vmcnt(0) lgkmcnt(0)
	v_mul_f32_e64 v16, |v15|, s94
	v_fma_f32 v17, |v15|, s94, -v16
	v_rndne_f32_e32 v18, v16
	v_fma_f32 v17, |v15|, s39, v17
	v_sub_f32_e32 v16, v16, v18
	v_add_f32_e32 v16, v16, v17
	v_exp_f32_e32 v16, v16
	v_cvt_i32_f32_e32 v17, v18
	v_cmp_ngt_f32_e64 s[52:53], |v15|, s22
	v_max_f32_e32 v14, v15, v15
	v_min_f32_e32 v14, 0, v14
	v_ldexp_f32 v16, v16, v17
	v_cndmask_b32_e64 v16, 0, v16, s[52:53]
	v_cmp_nlt_f32_e64 s[52:53], |v15|, s23
	s_nop 1
	v_cndmask_b32_e64 v15, v229, v16, s[52:53]
	v_add_f32_e32 v18, 1.0, v15
	v_add_f32_e32 v16, -1.0, v18
	v_sub_f32_e32 v17, v16, v18
	v_add_f32_e32 v17, 1.0, v17
	v_sub_f32_e32 v16, v15, v16
	v_add_f32_e32 v19, v16, v17
	v_frexp_mant_f32_e32 v16, v18
	v_cmp_gt_f32_e64 s[52:53], s60, v16
	v_cvt_f64_f32_e32 v[16:17], v18
	v_frexp_exp_i32_f64_e32 v16, v[16:17]
	v_subbrev_co_u32_e64 v16, s[52:53], 0, v16, s[52:53]
	v_sub_u32_e32 v17, 0, v16
	v_ldexp_f32 v18, v18, v17
	v_ldexp_f32 v17, v19, v17
	v_add_f32_e32 v19, -1.0, v18
	v_add_f32_e32 v20, 1.0, v19
	v_sub_f32_e32 v20, v18, v20
	v_add_f32_e32 v20, v17, v20
	v_add_f32_e32 v21, v19, v20
	v_sub_f32_e32 v19, v19, v21
	v_add_f32_e32 v19, v20, v19
	v_add_f32_e32 v20, 1.0, v18
	v_add_f32_e32 v22, -1.0, v20
	v_sub_f32_e32 v18, v18, v22
	v_add_f32_e32 v17, v17, v18
	v_add_f32_e32 v18, v20, v17
	v_sub_f32_e32 v20, v20, v18
	v_add_f32_e32 v17, v17, v20
	v_rcp_f32_e32 v20, v18
	v_cvt_f32_i32_e32 v16, v16
	v_cmp_neq_f32_e64 s[52:53], s25, v15
	v_mul_f32_e32 v22, v21, v20
	v_mul_f32_e32 v23, v18, v22
	v_fma_f32 v24, v22, v18, -v23
	v_fmac_f32_e32 v24, v22, v17
	v_add_f32_e32 v25, v23, v24
	v_sub_f32_e32 v26, v21, v25
	v_sub_f32_e32 v21, v21, v26
	v_sub_f32_e32 v23, v25, v23
	v_sub_f32_e32 v21, v21, v25
	v_add_f32_e32 v19, v19, v21
	v_sub_f32_e32 v21, v23, v24
	v_add_f32_e32 v19, v21, v19
	v_add_f32_e32 v21, v26, v19
	v_mul_f32_e32 v23, v20, v21
	v_mul_f32_e32 v24, v18, v23
	v_fma_f32 v18, v23, v18, -v24
	v_fmac_f32_e32 v18, v23, v17
	v_sub_f32_e32 v17, v26, v21
	v_add_f32_e32 v17, v19, v17
	v_add_f32_e32 v19, v24, v18
	v_sub_f32_e32 v25, v21, v19
	v_sub_f32_e32 v21, v21, v25
	v_sub_f32_e32 v24, v19, v24
	v_sub_f32_e32 v19, v21, v19
	v_add_f32_e32 v17, v17, v19
	v_sub_f32_e32 v18, v24, v18
	v_add_f32_e32 v17, v18, v17
	v_add_f32_e32 v18, v22, v23
	v_add_f32_e32 v17, v25, v17
	v_sub_f32_e32 v19, v18, v22
	v_mul_f32_e32 v17, v20, v17
	v_sub_f32_e32 v19, v23, v19
	v_add_f32_e32 v17, v19, v17
	v_mul_f32_e32 v22, 0x3f317218, v16
	v_add_f32_e32 v19, v18, v17
	v_fma_f32 v23, v16, s61, -v22
	v_mul_f32_e32 v20, v19, v19
	v_fmac_f32_e32 v23, 0xb102e308, v16
	v_sub_f32_e32 v16, v19, v18
	v_fmamk_f32 v21, v20, 0x3e9b6dac, v226
	v_sub_f32_e32 v16, v17, v16
	v_add_f32_e32 v17, v22, v23
	v_fmaak_f32 v21, v20, v21, 0x3f2aaada
	v_sub_f32_e32 v18, v17, v22
	v_ldexp_f32 v22, v19, 1
	v_mul_f32_e32 v19, v19, v20
	v_mul_f32_e32 v19, v19, v21
	v_add_f32_e32 v20, v22, v19
	v_sub_f32_e32 v21, v20, v22
	v_ldexp_f32 v16, v16, 1
	v_sub_f32_e32 v19, v19, v21
	v_add_f32_e32 v16, v16, v19
	v_add_f32_e32 v19, v20, v16
	v_sub_f32_e32 v20, v19, v20
	v_sub_f32_e32 v16, v16, v20
	v_add_f32_e32 v20, v17, v19
	v_sub_f32_e32 v21, v20, v17
	v_sub_f32_e32 v22, v20, v21
	v_sub_f32_e32 v18, v23, v18
	v_sub_f32_e32 v17, v17, v22
	v_sub_f32_e32 v19, v19, v21
	v_add_f32_e32 v17, v19, v17
	v_add_f32_e32 v19, v18, v16
	v_sub_f32_e32 v21, v19, v18
	v_sub_f32_e32 v22, v19, v21
	v_sub_f32_e32 v18, v18, v22
	v_sub_f32_e32 v16, v16, v21
	v_add_f32_e32 v17, v19, v17
	v_add_f32_e32 v16, v16, v18
	v_add_f32_e32 v18, v20, v17
	v_sub_f32_e32 v19, v18, v20
	v_sub_f32_e32 v17, v17, v19
	v_add_f32_e32 v16, v16, v17
	v_add_f32_e32 v16, v18, v16
	v_cndmask_b32_e64 v16, v229, v16, s[52:53]
	v_cmp_lt_f32_e64 s[52:53], |v15|, s95
	s_nop 1
	v_cndmask_b32_e64 v15, v16, v15, s[52:53]
	v_sub_f32_e32 v14, v14, v15
	ds_bpermute_b32 v15, v7, v14
	s_lshl_b32 s52, s3, 8
	s_mov_b32 s53, s37
	s_waitcnt lgkmcnt(0)
	v_add_f32_e32 v15, v14, v15
	v_cndmask_b32_e32 v14, v15, v14, vcc
	ds_bpermute_b32 v15, v8, v14
	s_waitcnt lgkmcnt(0)
	v_add_f32_e32 v15, v14, v15
	v_cndmask_b32_e64 v14, v15, v14, s[44:45]
	ds_bpermute_b32 v15, v9, v14
	s_waitcnt lgkmcnt(0)
	v_add_f32_e32 v15, v14, v15
	v_cndmask_b32_e64 v14, v15, v14, s[46:47]
	ds_bpermute_b32 v15, v10, v14
	s_waitcnt lgkmcnt(0)
	v_add_f32_e32 v15, v14, v15
	v_cndmask_b32_e64 v14, v15, v14, s[48:49]
	ds_bpermute_b32 v15, v11, v14
	s_waitcnt lgkmcnt(0)
	v_add_f32_e32 v15, v14, v15
	v_cndmask_b32_e64 v14, v15, v14, s[50:51]
	ds_bpermute_b32 v15, v12, v14
	s_waitcnt lgkmcnt(0)
	v_add_f32_e32 v15, v14, v15
	v_cndmask_b32_e64 v17, v15, v14, s[42:43]
	v_sub_f32_e32 v20, v13, v17
	ds_bpermute_b32 v14, v7, v20
	s_waitcnt lgkmcnt(0)
	v_max_f32_e32 v14, v14, v14
	v_max_f32_e32 v14, v20, v14
	v_cndmask_b32_e32 v14, v14, v20, vcc
	ds_bpermute_b32 v15, v8, v14
	s_waitcnt lgkmcnt(0)
	v_max_f32_e32 v15, v15, v15
	v_max_f32_e32 v15, v14, v15
	v_cndmask_b32_e64 v14, v15, v14, s[44:45]
	ds_bpermute_b32 v15, v9, v14
	s_waitcnt lgkmcnt(0)
	v_max_f32_e32 v15, v15, v15
	v_max_f32_e32 v15, v14, v15
	v_cndmask_b32_e64 v14, v15, v14, s[46:47]
	ds_bpermute_b32 v15, v10, v14
	s_waitcnt lgkmcnt(0)
	v_max_f32_e32 v15, v15, v15
	v_max_f32_e32 v15, v14, v15
	v_cndmask_b32_e64 v14, v15, v14, s[48:49]
	ds_bpermute_b32 v15, v11, v14
	s_waitcnt lgkmcnt(0)
	v_max_f32_e32 v15, v15, v15
	v_max_f32_e32 v15, v14, v15
	v_cndmask_b32_e64 v18, v15, v14, s[50:51]
	ds_bpermute_b32 v14, v12, v18
	v_max_f32_e32 v15, v18, v18
	s_waitcnt lgkmcnt(0)
	v_max_f32_e32 v14, v14, v14
	v_max_f32_e32 v19, v15, v14
	ds_bpermute_b32 v14, v6, v17
	v_cndmask_b32_e64 v21, v19, v18, s[42:43]
	v_lshl_add_u64 v[18:19], s[52:53], 2, v[2:3]
	global_store_dword v[18:19], v17, off sc1
	global_store_dword v[18:19], v20, off offset:256 sc1
	global_store_dword v[18:19], v21, off offset:512 sc1
	global_store_dword v[18:19], v13, off offset:768 sc1
	s_waitcnt lgkmcnt(0)
	v_sub_f32_e32 v15, v14, v17
	v_add_f32_e32 v15, v15, v13
	ds_bpermute_b32 v16, v189, v15
	s_waitcnt lgkmcnt(0)
	v_max_f32_e32 v16, v16, v16
	v_max_f32_e32 v15, v15, v16
	ds_bpermute_b32 v16, v191, v15
	s_waitcnt lgkmcnt(0)
	v_max_f32_e32 v16, v16, v16
	v_max_f32_e32 v15, v15, v16
	ds_bpermute_b32 v16, v209, v15
	s_waitcnt lgkmcnt(0)
	v_max_f32_e32 v16, v16, v16
	v_max_f32_e32 v15, v15, v16
	ds_bpermute_b32 v16, v210, v15
	s_waitcnt lgkmcnt(0)
	v_max_f32_e32 v16, v16, v16
	v_max_f32_e32 v15, v15, v16
	ds_bpermute_b32 v16, v211, v15
	s_waitcnt lgkmcnt(0)
	v_max_f32_e32 v16, v16, v16
	v_max_f32_e32 v15, v15, v16
	ds_bpermute_b32 v16, v212, v15
	s_and_saveexec_b64 s[52:53], vcc
	s_cbranch_execz .LBB0_179
	s_lshl_b32 s3, s3, 2
	s_add_i32 s3, s3, 0
	s_add_i32 s5, s3, 0x21900
	s_waitcnt lgkmcnt(0)
	v_max_f32_e32 v13, v16, v16
	v_max_f32_e32 v15, v15, v15
	s_add_i32 s3, s3, 0x21980
	v_max_f32_e32 v13, v15, v13
	v_mov_b32_e32 v15, s5
	ds_write_b32 v15, v14
	v_mov_b32_e32 v14, s3
	ds_write_b32 v14, v13
.LBB0_179:
	s_or_b64 exec, exec, s[52:53]
	s_add_i32 s3, s12, 24
	s_lshl_b32 s14, s3, 6
	s_mov_b32 s15, s37
	v_lshl_add_u64 v[0:1], v[0:1], 0, s[14:15]
	v_lshlrev_b64 v[0:1], 7, v[0:1]
	v_lshl_add_u64 v[0:1], s[16:17], 0, v[0:1]
	v_lshl_add_u64 v[14:15], v[0:1], 0, s[36:37]
	v_mov_b32_e32 v0, v36
	v_mov_b32_e32 v13, v37
	s_lshl_b32 s36, s3, 8
	v_lshl_add_u64 v[2:3], s[36:37], 2, v[2:3]
	s_waitcnt vmcnt(0)
	v_mul_f32_e64 v14, |v13|, s94
	v_fma_f32 v15, |v13|, s94, -v14
	s_waitcnt lgkmcnt(0)
	v_rndne_f32_e32 v16, v14
	v_fma_f32 v15, |v13|, s39, v15
	v_sub_f32_e32 v14, v14, v16
	v_add_f32_e32 v14, v14, v15
	v_exp_f32_e32 v14, v14
	v_cvt_i32_f32_e32 v15, v16
	v_cmp_ngt_f32_e64 s[52:53], |v13|, s22
	v_max_f32_e32 v1, v13, v13
	v_min_f32_e32 v1, 0, v1
	v_ldexp_f32 v14, v14, v15
	v_cndmask_b32_e64 v14, 0, v14, s[52:53]
	v_cmp_nlt_f32_e64 s[52:53], |v13|, s23
	s_nop 1
	v_cndmask_b32_e64 v13, v229, v14, s[52:53]
	v_add_f32_e32 v16, 1.0, v13
	v_add_f32_e32 v14, -1.0, v16
	v_sub_f32_e32 v15, v14, v16
	v_add_f32_e32 v15, 1.0, v15
	v_sub_f32_e32 v14, v13, v14
	v_add_f32_e32 v17, v14, v15
	v_frexp_mant_f32_e32 v14, v16
	v_cmp_gt_f32_e64 s[52:53], s60, v14
	v_cvt_f64_f32_e32 v[14:15], v16
	v_frexp_exp_i32_f64_e32 v14, v[14:15]
	v_subbrev_co_u32_e64 v14, s[52:53], 0, v14, s[52:53]
	v_sub_u32_e32 v15, 0, v14
	v_ldexp_f32 v16, v16, v15
	v_ldexp_f32 v15, v17, v15
	v_add_f32_e32 v17, -1.0, v16
	v_add_f32_e32 v18, 1.0, v17
	v_sub_f32_e32 v18, v16, v18
	v_add_f32_e32 v18, v15, v18
	v_add_f32_e32 v19, v17, v18
	v_sub_f32_e32 v17, v17, v19
	v_add_f32_e32 v17, v18, v17
	v_add_f32_e32 v18, 1.0, v16
	v_add_f32_e32 v20, -1.0, v18
	v_sub_f32_e32 v16, v16, v20
	v_add_f32_e32 v15, v15, v16
	v_add_f32_e32 v16, v18, v15
	v_sub_f32_e32 v18, v18, v16
	v_add_f32_e32 v15, v15, v18
	v_rcp_f32_e32 v18, v16
	v_cvt_f32_i32_e32 v14, v14
	v_cmp_neq_f32_e64 s[52:53], s25, v13
	v_mul_f32_e32 v20, v19, v18
	v_mul_f32_e32 v21, v16, v20
	v_fma_f32 v22, v20, v16, -v21
	v_fmac_f32_e32 v22, v20, v15
	v_add_f32_e32 v23, v21, v22
	v_sub_f32_e32 v24, v19, v23
	v_sub_f32_e32 v19, v19, v24
	v_sub_f32_e32 v21, v23, v21
	v_sub_f32_e32 v19, v19, v23
	v_add_f32_e32 v17, v17, v19
	v_sub_f32_e32 v19, v21, v22
	v_add_f32_e32 v17, v19, v17
	v_add_f32_e32 v19, v24, v17
	v_mul_f32_e32 v21, v18, v19
	v_mul_f32_e32 v22, v16, v21
	v_fma_f32 v16, v21, v16, -v22
	v_fmac_f32_e32 v16, v21, v15
	v_sub_f32_e32 v15, v24, v19
	v_add_f32_e32 v15, v17, v15
	v_add_f32_e32 v17, v22, v16
	v_sub_f32_e32 v23, v19, v17
	v_sub_f32_e32 v19, v19, v23
	v_sub_f32_e32 v22, v17, v22
	v_sub_f32_e32 v17, v19, v17
	v_add_f32_e32 v15, v15, v17
	v_sub_f32_e32 v16, v22, v16
	v_add_f32_e32 v15, v16, v15
	v_add_f32_e32 v16, v20, v21
	v_add_f32_e32 v15, v23, v15
	v_sub_f32_e32 v17, v16, v20
	v_mul_f32_e32 v15, v18, v15
	v_sub_f32_e32 v17, v21, v17
	v_add_f32_e32 v15, v17, v15
	v_mul_f32_e32 v20, 0x3f317218, v14
	v_add_f32_e32 v17, v16, v15
	v_fma_f32 v21, v14, s61, -v20
	v_mul_f32_e32 v18, v17, v17
	v_fmac_f32_e32 v21, 0xb102e308, v14
	v_sub_f32_e32 v14, v17, v16
	v_fmamk_f32 v19, v18, 0x3e9b6dac, v226
	v_sub_f32_e32 v14, v15, v14
	v_add_f32_e32 v15, v20, v21
	v_fmaak_f32 v19, v18, v19, 0x3f2aaada
	v_sub_f32_e32 v16, v15, v20
	v_ldexp_f32 v20, v17, 1
	v_mul_f32_e32 v17, v17, v18
	v_mul_f32_e32 v17, v17, v19
	v_add_f32_e32 v18, v20, v17
	v_sub_f32_e32 v19, v18, v20
	v_ldexp_f32 v14, v14, 1
	v_sub_f32_e32 v17, v17, v19
	v_add_f32_e32 v14, v14, v17
	v_add_f32_e32 v17, v18, v14
	v_sub_f32_e32 v18, v17, v18
	v_sub_f32_e32 v14, v14, v18
	v_add_f32_e32 v18, v15, v17
	v_sub_f32_e32 v19, v18, v15
	v_sub_f32_e32 v20, v18, v19
	v_sub_f32_e32 v16, v21, v16
	v_sub_f32_e32 v15, v15, v20
	v_sub_f32_e32 v17, v17, v19
	v_add_f32_e32 v15, v17, v15
	v_add_f32_e32 v17, v16, v14
	v_sub_f32_e32 v19, v17, v16
	v_sub_f32_e32 v20, v17, v19
	v_sub_f32_e32 v16, v16, v20
	v_sub_f32_e32 v14, v14, v19
	v_add_f32_e32 v15, v17, v15
	v_add_f32_e32 v14, v14, v16
	v_add_f32_e32 v16, v18, v15
	v_sub_f32_e32 v17, v16, v18
	v_sub_f32_e32 v15, v15, v17
	v_add_f32_e32 v14, v14, v15
	v_add_f32_e32 v14, v16, v14
	v_cndmask_b32_e64 v14, v229, v14, s[52:53]
	v_cmp_lt_f32_e64 s[52:53], |v13|, s95
	s_nop 1
	v_cndmask_b32_e64 v13, v14, v13, s[52:53]
	v_sub_f32_e32 v1, v1, v13
	ds_bpermute_b32 v13, v7, v1
	s_waitcnt lgkmcnt(0)
	v_add_f32_e32 v13, v1, v13
	v_cndmask_b32_e32 v1, v13, v1, vcc
	ds_bpermute_b32 v13, v8, v1
	s_waitcnt lgkmcnt(0)
	v_add_f32_e32 v13, v1, v13
	v_cndmask_b32_e64 v1, v13, v1, s[44:45]
	ds_bpermute_b32 v13, v9, v1
	s_waitcnt lgkmcnt(0)
	v_add_f32_e32 v13, v1, v13
	v_cndmask_b32_e64 v1, v13, v1, s[46:47]
	ds_bpermute_b32 v13, v10, v1
	s_waitcnt lgkmcnt(0)
	v_add_f32_e32 v13, v1, v13
	v_cndmask_b32_e64 v1, v13, v1, s[48:49]
	ds_bpermute_b32 v13, v11, v1
	s_waitcnt lgkmcnt(0)
	v_add_f32_e32 v13, v1, v13
	v_cndmask_b32_e64 v1, v13, v1, s[50:51]
	ds_bpermute_b32 v13, v12, v1
	s_waitcnt lgkmcnt(0)
	v_add_f32_e32 v13, v1, v13
	v_cndmask_b32_e64 v13, v13, v1, s[42:43]
	v_sub_f32_e32 v14, v0, v13
	ds_bpermute_b32 v1, v7, v14
	s_waitcnt lgkmcnt(0)
	v_max_f32_e32 v1, v1, v1
	v_max_f32_e32 v1, v14, v1
	v_cndmask_b32_e32 v1, v1, v14, vcc
	ds_bpermute_b32 v7, v8, v1
	s_waitcnt lgkmcnt(0)
	v_max_f32_e32 v7, v7, v7
	v_max_f32_e32 v7, v1, v7
	v_cndmask_b32_e64 v1, v7, v1, s[44:45]
	ds_bpermute_b32 v7, v9, v1
	s_waitcnt lgkmcnt(0)
	v_max_f32_e32 v7, v7, v7
	v_max_f32_e32 v7, v1, v7
	v_cndmask_b32_e64 v1, v7, v1, s[46:47]
	ds_bpermute_b32 v7, v10, v1
	s_waitcnt lgkmcnt(0)
	v_max_f32_e32 v7, v7, v7
	v_max_f32_e32 v7, v1, v7
	v_cndmask_b32_e64 v1, v7, v1, s[48:49]
	ds_bpermute_b32 v7, v11, v1
	s_waitcnt lgkmcnt(0)
	v_max_f32_e32 v7, v7, v7
	v_max_f32_e32 v7, v1, v7
	v_cndmask_b32_e64 v8, v7, v1, s[50:51]
	ds_bpermute_b32 v1, v12, v8
	v_max_f32_e32 v7, v8, v8
	s_waitcnt lgkmcnt(0)
	v_max_f32_e32 v1, v1, v1
	v_max_f32_e32 v9, v7, v1
	ds_bpermute_b32 v1, v6, v13
	v_cndmask_b32_e64 v8, v9, v8, s[42:43]
	global_store_dword v[2:3], v13, off sc1
	global_store_dword v[2:3], v14, off offset:256 sc1
	global_store_dword v[2:3], v8, off offset:512 sc1
	global_store_dword v[2:3], v0, off offset:768 sc1
	s_waitcnt lgkmcnt(0)
	v_sub_f32_e32 v6, v1, v13
	v_add_f32_e32 v6, v6, v0
	ds_bpermute_b32 v7, v189, v6
	s_waitcnt lgkmcnt(0)
	v_max_f32_e32 v7, v7, v7
	v_max_f32_e32 v6, v6, v7
	ds_bpermute_b32 v7, v191, v6
	s_waitcnt lgkmcnt(0)
	v_max_f32_e32 v7, v7, v7
	v_max_f32_e32 v6, v6, v7
	ds_bpermute_b32 v7, v209, v6
	s_waitcnt lgkmcnt(0)
	v_max_f32_e32 v7, v7, v7
	v_max_f32_e32 v6, v6, v7
	ds_bpermute_b32 v7, v210, v6
	s_waitcnt lgkmcnt(0)
	v_max_f32_e32 v7, v7, v7
	v_max_f32_e32 v6, v6, v7
	ds_bpermute_b32 v7, v211, v6
	s_waitcnt lgkmcnt(0)
	v_max_f32_e32 v7, v7, v7
	v_max_f32_e32 v6, v6, v7
	ds_bpermute_b32 v7, v212, v6
	s_and_saveexec_b64 s[44:45], vcc
	s_cbranch_execz .LBB0_181
	s_lshl_b32 s3, s3, 2
	s_add_i32 s3, s3, 0
	s_add_i32 s5, s3, 0x21900
	s_waitcnt lgkmcnt(0)
	v_max_f32_e32 v0, v7, v7
	v_max_f32_e32 v2, v6, v6
	s_add_i32 s3, s3, 0x21980
	v_max_f32_e32 v0, v2, v0
	v_mov_b32_e32 v2, s5
	ds_write_b32 v2, v1
	v_mov_b32_e32 v1, s3
	ds_write_b32 v1, v0
